# NSA selected-block loop: same treatment (K prefetch, max3, lazy rescale, all V reads early, no in-loop vmcnt drain)
# speedup vs baseline: 1.0112x; 1.0112x over previous
.LBB0_1315:
	s_or_b64 exec, exec, s[10:11]
	v_mov_b32_e32 v36, v149
	v_readlane_b32 s6, v254, 3
	s_waitcnt lgkmcnt(0)
	s_barrier
	s_waitcnt vmcnt(0)
	v_mov_b32_e32 v34, s6
	v_and_b32_e32 v0, 31, v36
	v_lshl_add_u32 v0, v0, 3, s91
	ds_read_b64 v[34:35], v34
	ds_read_b64 v[98:99], v0
	s_lshl_b32 s6, s29, 19
	v_readlane_b32 s10, v254, 18
	v_readlane_b32 s11, v254, 19
	s_add_u32 s12, s10, s6
	s_addc_u32 s13, s11, 0
	s_lshl_b32 s6, s30, 19
	s_add_u32 s14, s10, s6
	s_addc_u32 s15, s11, 0
	s_waitcnt lgkmcnt(1)
	v_readfirstlane_b32 s6, v34
	v_readfirstlane_b32 s7, v35
	s_add_u32 s10, s6, -1
	s_addc_u32 s11, s7, -1
	s_and_b64 s[10:11], s[10:11], s[6:7]
	s_ff1_i32_b64 s16, s[6:7]
	s_cmp_lg_u64 s[6:7], 0
	s_cselect_b32 s6, s16, -1
	s_ff1_i32_b64 s7, s[10:11]
	s_cmp_lg_u64 s[10:11], 0
	s_cselect_b32 s7, s7, -1
	s_lshl_b32 s16, s6, 6
	s_ashr_i32 s17, s16, 31
	v_bfe_u32 v37, v36, 3, 3
	s_mul_i32 s17, s82, s17
	s_mul_hi_u32 s18, s82, s16
	v_or_b32_e32 v0, s77, v37
	s_add_i32 s17, s18, s17
	s_mul_i32 s18, s83, s16
	v_ashrrev_i32_e32 v39, 1, v0
	s_add_i32 s17, s17, s18
	s_mul_i32 s16, s82, s16
	v_xor_b32_e32 v34, v39, v36
	s_lshl_b64 s[16:17], s[16:17], 1
	v_mul_lo_u32 v40, v0, s82
	v_lshlrev_b32_e32 v0, 3, v34
	s_add_u32 s18, s12, s16
	v_and_b32_e32 v0, 56, v0
	s_addc_u32 s19, s13, s17
	v_add_u32_e32 v0, v0, v40
	v_lshl_add_u64 v[34:35], v[0:1], 1, s[18:19]
	v_and_b32_e32 v38, 7, v36
	s_mov_b32 s18, m0
	s_mov_b32 m0, s93
	s_nop 0
	global_load_lds_dwordx4 v[34:35], off
	s_mov_b32 m0, s18
	v_lshlrev_b32_e32 v34, 2, v39
	s_add_u32 s16, s14, s16
	v_bitop3_b32 v34, v34, v38, 4 bitop3:0x6c
	s_addc_u32 s17, s15, s17
	v_lshl_add_u32 v34, v34, 3, v40
	v_mov_b32_e32 v35, v1
	v_lshl_add_u64 v[38:39], v[34:35], 1, s[16:17]
	s_mov_b32 s16, m0
	s_mov_b32 m0, s94
	s_nop 0
	global_load_lds_dwordx4 v[38:39], off
	s_mov_b32 m0, s16
	s_cmp_lt_i32 s7, 0
	s_cbranch_scc1 .LBB0_1317
	s_lshl_b32 s16, s7, 6
	s_mul_i32 s17, s83, s16
	s_mul_hi_u32 s18, s82, s16
	s_add_i32 s17, s18, s17
	s_mul_i32 s16, s82, s16
	s_lshl_b64 s[16:17], s[16:17], 1
	s_add_u32 s18, s12, s16
	s_addc_u32 s19, s13, s17
	s_add_u32 s16, s14, s16
	s_addc_u32 s17, s15, s17
	v_lshl_add_u64 v[38:39], v[0:1], 1, s[18:19]
	s_mov_b32 s18, m0
	s_mov_b32 m0, s95
	s_nop 0
	global_load_lds_dwordx4 v[38:39], off
	s_mov_b32 m0, s18
	v_lshl_add_u64 v[38:39], v[34:35], 1, s[16:17]
	s_mov_b32 s16, m0
	s_mov_b32 m0, s98
	s_nop 0
	global_load_lds_dwordx4 v[38:39], off
	s_mov_b32 m0, s16

.LBB0_1328:
	s_lshl_b32 s13, s14, 14
	s_add_i32 s12, s13, 0
	v_add3_u32 v0, s12, v110, v111
	v_add_u32_e32 v104, v0, v112
	v_add_u32_e32 v105, v0, v113
	v_add_u32_e32 v106, v0, v114
	v_add_u32_e32 v107, v0, v115
	ds_read_b128 v[192:195], v104
	ds_read_b128 v[196:199], v104 offset:4096
	ds_read_b128 v[200:203], v105
	ds_read_b128 v[204:207], v105 offset:4096
	ds_read_b128 v[208:211], v106
	ds_read_b128 v[212:215], v106 offset:4096
	ds_read_b128 v[216:219], v107
	ds_read_b128 v[220:223], v107 offset:4096
	s_lshl_b32 s15, s6, 6
	s_sub_i32 s16, s54, s15
	s_cmpk_gt_i32 s16, 0x70
	s_waitcnt lgkmcnt(7)
	v_mfma_f32_32x32x16_bf16 v[66:81], v[192:195], v[130:133], 0
	s_waitcnt lgkmcnt(6)
	v_mfma_f32_32x32x16_bf16 v[82:97], v[196:199], v[130:133], 0
	s_waitcnt lgkmcnt(5)
	v_mfma_f32_32x32x16_bf16 v[66:81], v[200:203], v[134:137], v[66:81]
	s_waitcnt lgkmcnt(4)
	v_mfma_f32_32x32x16_bf16 v[82:97], v[204:207], v[134:137], v[82:97]
	s_waitcnt lgkmcnt(3)
	v_mfma_f32_32x32x16_bf16 v[66:81], v[208:211], v[138:141], v[66:81]
	s_waitcnt lgkmcnt(2)
	v_mfma_f32_32x32x16_bf16 v[82:97], v[212:215], v[138:141], v[82:97]
	s_waitcnt lgkmcnt(1)
	v_mfma_f32_32x32x16_bf16 v[66:81], v[216:219], v[142:145], v[66:81]
	s_waitcnt lgkmcnt(0)
	v_mfma_f32_32x32x16_bf16 v[82:97], v[220:223], v[142:145], v[82:97]
	s_cbranch_scc1 .LBB0_1330
	v_or_b32_e32 v0, s15, v116
	v_sub_u32_e32 v0, v156, v0
	v_add_u32_e32 v125, -1, v0
	v_subrev_u32_e32 v191, 33, v0
	v_subrev_u32_e32 v194, 32, v0
	v_subrev_u32_e32 v198, 34, v0
	v_med3_i32 v104, v0, 0, v181
	v_med3_i32 v105, v125, 0, v181
	v_med3_i32 v106, v194, 0, v181
	v_med3_i32 v107, v191, 0, v181
	v_add_u32_e32 v195, -3, v0
	v_add_u32_e32 v196, -2, v0
	v_subrev_u32_e32 v197, 35, v0
	v_med3_i32 v126, v198, 0, v181
	v_lshl_add_u32 v104, v104, 2, s5
	v_lshl_add_u32 v105, v105, 2, s5
	v_lshl_add_u32 v106, v106, 2, s5
	v_lshl_add_u32 v107, v107, 2, s5
	v_med3_i32 v108, v196, 0, v181
	v_med3_i32 v109, v195, 0, v181
	v_lshl_add_u32 v158, v126, 2, s5
	v_med3_i32 v126, v197, 0, v181
	v_lshl_add_u32 v108, v108, 2, s5
	v_lshl_add_u32 v109, v109, 2, s5
	v_lshl_add_u32 v159, v126, 2, s5
	ds_read_b32 v126, v104
	ds_read_b32 v127, v105
	ds_read_b32 v106, v106
	ds_read_b32 v107, v107
	ds_read_b32 v128, v108
	ds_read_b32 v129, v109
	ds_read_b32 v104, v158
	ds_read_b32 v105, v159
	v_subrev_u32_e32 v202, 40, v0
	v_subrev_u32_e32 v201, 41, v0
	v_med3_i32 v158, v202, 0, v181
	v_lshl_add_u32 v160, v158, 2, s5
	v_med3_i32 v158, v201, 0, v181
	v_add_u32_e32 v204, -10, v0
	v_lshl_add_u32 v161, v158, 2, s5
	v_add_u32_e32 v203, -11, v0
	v_med3_i32 v158, v204, 0, v181
	v_add_u32_e32 v199, -9, v0
	v_add_u32_e32 v200, -8, v0
	v_lshl_add_u32 v162, v158, 2, s5
	v_med3_i32 v158, v203, 0, v181
	v_subrev_u32_e32 v206, 42, v0
	v_med3_i32 v108, v200, 0, v181
	v_med3_i32 v109, v199, 0, v181
	v_lshl_add_u32 v163, v158, 2, s5
	v_subrev_u32_e32 v205, 43, v0
	v_med3_i32 v158, v206, 0, v181
	v_lshl_add_u32 v108, v108, 2, s5
	v_lshl_add_u32 v109, v109, 2, s5
	v_lshl_add_u32 v164, v158, 2, s5
	v_med3_i32 v158, v205, 0, v181
	v_lshl_add_u32 v165, v158, 2, s5
	ds_read_b32 v158, v108
	ds_read_b32 v159, v109
	ds_read_b32 v160, v160
	ds_read_b32 v161, v161
	ds_read_b32 v162, v162
	ds_read_b32 v163, v163
	ds_read_b32 v108, v164
	ds_read_b32 v109, v165
	v_subrev_u32_e32 v207, 17, v0
	v_add_u32_e32 v208, -16, v0
	v_subrev_u32_e32 v209, 49, v0
	v_subrev_u32_e32 v210, 48, v0
	v_subrev_u32_e32 v211, 19, v0
	v_subrev_u32_e32 v212, 18, v0
	v_subrev_u32_e32 v213, 51, v0
	v_subrev_u32_e32 v214, 50, v0
	v_med3_i32 v164, v208, 0, v181
	v_med3_i32 v165, v207, 0, v181
	v_med3_i32 v166, v210, 0, v181
	v_med3_i32 v167, v209, 0, v181
	v_med3_i32 v168, v212, 0, v181
	v_med3_i32 v169, v211, 0, v181
	v_med3_i32 v170, v214, 0, v181
	v_med3_i32 v171, v213, 0, v181
	v_lshl_add_u32 v164, v164, 2, s5
	v_lshl_add_u32 v165, v165, 2, s5
	v_lshl_add_u32 v166, v166, 2, s5
	v_lshl_add_u32 v167, v167, 2, s5
	v_lshl_add_u32 v168, v168, 2, s5
	v_lshl_add_u32 v169, v169, 2, s5
	v_lshl_add_u32 v170, v170, 2, s5
	v_lshl_add_u32 v171, v171, 2, s5
	ds_read_b32 v164, v164
	ds_read_b32 v165, v165
	ds_read_b32 v166, v166
	ds_read_b32 v167, v167
	ds_read_b32 v168, v168
	ds_read_b32 v169, v169
	ds_read_b32 v170, v170
	ds_read_b32 v171, v171
	s_waitcnt lgkmcnt(14)
	v_pk_add_f32 v[68:69], v[68:69], v[128:129]
	v_cmp_gt_u32_e32 vcc, 2.0, v195
	v_pk_add_f32 v[66:67], v[66:67], v[126:127]
	s_waitcnt lgkmcnt(10)
	v_pk_add_f32 v[72:73], v[72:73], v[162:163]
	v_cndmask_b32_e32 v69, v182, v69, vcc
	v_cmp_gt_u32_e32 vcc, 2.0, v196
	v_pk_add_f32 v[70:71], v[70:71], v[158:159]
	v_subrev_u32_e32 v215, 25, v0
	v_cndmask_b32_e32 v68, v182, v68, vcc
	v_cmp_gt_u32_e32 vcc, 2.0, v125
	v_subrev_u32_e32 v216, 24, v0
	v_subrev_u32_e32 v217, 57, v0
	v_cndmask_b32_e32 v67, v182, v67, vcc
	v_cmp_gt_u32_e32 vcc, 2.0, v0
	v_subrev_u32_e32 v218, 56, v0
	v_subrev_u32_e32 v219, 27, v0
	v_cndmask_b32_e32 v66, v182, v66, vcc
	v_cmp_gt_u32_e32 vcc, 2.0, v203
	v_subrev_u32_e32 v220, 26, v0
	v_subrev_u32_e32 v221, 59, v0
	v_cndmask_b32_e32 v73, v182, v73, vcc
	v_cmp_gt_u32_e32 vcc, 2.0, v204
	v_subrev_u32_e32 v222, 58, v0
	v_med3_i32 v172, v216, 0, v181
	v_cndmask_b32_e32 v72, v182, v72, vcc
	v_cmp_gt_u32_e32 vcc, 2.0, v199
	v_med3_i32 v173, v215, 0, v181
	v_med3_i32 v174, v218, 0, v181
	v_cndmask_b32_e32 v71, v182, v71, vcc
	v_cmp_gt_u32_e32 vcc, 2.0, v200
	v_med3_i32 v175, v217, 0, v181
	v_med3_i32 v178, v220, 0, v181
	v_med3_i32 v179, v219, 0, v181
	v_med3_i32 v192, v222, 0, v181
	v_med3_i32 v193, v221, 0, v181
	s_waitcnt lgkmcnt(2)
	v_pk_add_f32 v[76:77], v[76:77], v[168:169]
	v_cndmask_b32_e32 v70, v182, v70, vcc
	v_cmp_gt_u32_e32 vcc, 2.0, v211
	v_lshl_add_u32 v172, v172, 2, s5
	v_lshl_add_u32 v173, v173, 2, s5
	v_lshl_add_u32 v174, v174, 2, s5
	v_lshl_add_u32 v175, v175, 2, s5
	v_lshl_add_u32 v178, v178, 2, s5
	v_lshl_add_u32 v179, v179, 2, s5
	v_lshl_add_u32 v192, v192, 2, s5
	v_lshl_add_u32 v193, v193, 2, s5
	v_cndmask_b32_e32 v77, v182, v77, vcc
	v_cmp_gt_u32_e32 vcc, 2.0, v212
	ds_read_b32 v172, v172
	ds_read_b32 v173, v173
	ds_read_b32 v174, v174
	ds_read_b32 v178, v178
	ds_read_b32 v179, v179
	ds_read_b32 v192, v192
	ds_read_b32 v193, v193
	ds_read_b32 v175, v175
	v_pk_add_f32 v[74:75], v[74:75], v[164:165]
	v_cndmask_b32_e32 v76, v182, v76, vcc
	v_cmp_gt_u32_e32 vcc, 2.0, v207
	s_waitcnt lgkmcnt(3)
	v_pk_add_f32 v[80:81], v[80:81], v[178:179]
	v_pk_add_f32 v[78:79], v[78:79], v[172:173]
	v_cndmask_b32_e32 v75, v182, v75, vcc
	v_cmp_gt_u32_e32 vcc, 2.0, v208
	v_pk_add_f32 v[84:85], v[84:85], v[104:105]
	v_pk_add_f32 v[82:83], v[82:83], v[106:107]
	v_cndmask_b32_e32 v74, v182, v74, vcc
	v_cmp_gt_u32_e32 vcc, 2.0, v219
	v_pk_add_f32 v[88:89], v[88:89], v[108:109]
	v_pk_add_f32 v[86:87], v[86:87], v[160:161]
	v_cndmask_b32_e32 v81, v182, v81, vcc
	v_cmp_gt_u32_e32 vcc, 2.0, v220
	v_pk_add_f32 v[92:93], v[92:93], v[170:171]
	v_pk_add_f32 v[90:91], v[90:91], v[166:167]
	v_cndmask_b32_e32 v80, v182, v80, vcc
	v_cmp_gt_u32_e32 vcc, 2.0, v215
	s_waitcnt lgkmcnt(1)
	v_pk_add_f32 v[96:97], v[96:97], v[192:193]
	s_waitcnt lgkmcnt(0)
	v_pk_add_f32 v[94:95], v[94:95], v[174:175]
	v_cndmask_b32_e32 v79, v182, v79, vcc
	v_cmp_gt_u32_e32 vcc, 2.0, v216
	s_nop 1
	v_cndmask_b32_e32 v78, v182, v78, vcc
	v_cmp_gt_u32_e32 vcc, 2.0, v197
	s_nop 1
	v_cndmask_b32_e32 v85, v182, v85, vcc
	v_cmp_gt_u32_e32 vcc, 2.0, v198
	s_nop 1
	v_cndmask_b32_e32 v84, v182, v84, vcc
	v_cmp_gt_u32_e32 vcc, 2.0, v191
	s_nop 1
	v_cndmask_b32_e32 v83, v182, v83, vcc
	v_cmp_gt_u32_e32 vcc, 2.0, v194
	s_nop 1
	v_cndmask_b32_e32 v82, v182, v82, vcc
	v_cmp_gt_u32_e32 vcc, 2.0, v205
	s_nop 1
	v_cndmask_b32_e32 v89, v182, v89, vcc
	v_cmp_gt_u32_e32 vcc, 2.0, v206
	s_nop 1
	v_cndmask_b32_e32 v88, v182, v88, vcc
	v_cmp_gt_u32_e32 vcc, 2.0, v201
	s_nop 1
	v_cndmask_b32_e32 v87, v182, v87, vcc
	v_cmp_gt_u32_e32 vcc, 2.0, v202
	s_nop 1
	v_cndmask_b32_e32 v86, v182, v86, vcc
	v_cmp_gt_u32_e32 vcc, 2.0, v213
	s_nop 1
	v_cndmask_b32_e32 v93, v182, v93, vcc
	v_cmp_gt_u32_e32 vcc, 2.0, v214
	s_nop 1
	v_cndmask_b32_e32 v92, v182, v92, vcc
	v_cmp_gt_u32_e32 vcc, 2.0, v209
	s_nop 1
	v_cndmask_b32_e32 v91, v182, v91, vcc
	v_cmp_gt_u32_e32 vcc, 2.0, v210
	s_nop 1
	v_cndmask_b32_e32 v90, v182, v90, vcc
	v_cmp_gt_u32_e32 vcc, 2.0, v221
	s_nop 1
	v_cndmask_b32_e32 v97, v182, v97, vcc
	v_cmp_gt_u32_e32 vcc, 2.0, v222
	s_nop 1
	v_cndmask_b32_e32 v96, v182, v96, vcc
	v_cmp_gt_u32_e32 vcc, 2.0, v217
	s_nop 1
	v_cndmask_b32_e32 v95, v182, v95, vcc
	v_cmp_gt_u32_e32 vcc, 2.0, v218
	s_nop 1
	v_cndmask_b32_e32 v94, v182, v94, vcc
.LBB0_1330:
	v_add3_u32 v0, s12, v117, v118
	v_add3_u32 v0, v0, v119, v120
	v_add_u32_e32 v174, v0, v121
	v_add_u32_e32 v175, v0, v122
	ds_read_b64_tr_b16 v[224:225], v174 offset:8192
	ds_read_b64_tr_b16 v[226:227], v174 offset:9216
	ds_read_b64_tr_b16 v[228:229], v175 offset:8192
	ds_read_b64_tr_b16 v[230:231], v175 offset:9216
	ds_read_b64_tr_b16 v[232:233], v174 offset:10240
	ds_read_b64_tr_b16 v[234:235], v174 offset:11264
	ds_read_b64_tr_b16 v[236:237], v175 offset:10240
	ds_read_b64_tr_b16 v[238:239], v175 offset:11264
	s_ff1_i32_b64 s15, s[10:11]
	s_cmp_lg_u64 s[10:11], 0
	s_cselect_b32 s15, s15, -1
	v_max3_f32 v0, v66, v67, v68
	v_max3_f32 v104, v69, v70, v71
	v_max3_f32 v105, v72, v73, v74
	v_max3_f32 v106, v75, v76, v77
	v_max3_f32 v0, v0, v78, v79
	v_max3_f32 v104, v104, v80, v81
	v_max3_f32 v105, v105, v82, v83
	v_max3_f32 v106, v106, v84, v85
	v_max3_f32 v0, v0, v86, v87
	v_max3_f32 v104, v104, v88, v89
	v_max3_f32 v105, v105, v90, v91
	v_max3_f32 v106, v106, v92, v93
	v_max3_f32 v0, v0, v94, v95
	v_max3_f32 v104, v104, v96, v97
	v_max3_f32 v0, v0, v104, v105
	v_max_f32_e32 v104, v0, v106
	v_mov_b32_e32 v105, v104
	s_cmp_lt_i32 s15, 0
	s_nop 0
	v_permlane32_swap_b32 v104, v105
	s_cbranch_scc1 .LBB0_1332
	s_lshl_b32 s16, s15, 6
	s_add_i32 s13, s13, 0xc000
	s_mul_i32 s17, s83, s16
	s_mul_hi_u32 s19, s82, s16
	s_and_b32 s13, s13, 0xc000
	s_add_i32 s17, s19, s17
	s_mul_i32 s16, s82, s16
	s_add_i32 s13, s13, 0
	s_lshl_b64 s[16:17], s[16:17], 1
	v_lshl_add_u64 v[106:107], v[100:101], 0, s[16:17]
	s_add_i32 s13, s92, s13
	s_mov_b32 s19, m0
	s_mov_b32 m0, s13
	s_nop 0
	global_load_lds_dwordx4 v[106:107], off
	s_mov_b32 m0, s19
	v_lshl_add_u64 v[106:107], v[102:103], 0, s[16:17]
	s_addk_i32 s13, 0x2000
	s_mov_b32 s16, m0
	s_mov_b32 m0, s13
	s_nop 0
	global_load_lds_dwordx4 v[106:107], off
	s_mov_b32 m0, s16
.LBB0_1332:
	v_lshrrev_b64 v[106:107], s6, v[98:99]
	v_max_f32_e32 v104, v104, v105
	v_and_b32_e32 v0, 1, v106
	v_cmp_eq_u64_e64 s[16:17], 0, v[0:1]
	s_nop 1
	v_cndmask_b32_e64 v105, v104, v182, s[16:17]
	v_sub_f32_e32 v0, v105, v124
	v_cmp_lt_f32_e32 vcc, 0x41000000, v0
	s_cbranch_vccnz .Lslc_rescale
.Lslc_exp:
	v_cndmask_b32_e64 v105, v124, v180, s[16:17]
	v_sub_f32_e32 v104, v66, v105
	v_sub_f32_e32 v106, v67, v105
	v_sub_f32_e32 v107, v68, v105
	v_sub_f32_e32 v0, v69, v105
	v_exp_f32_e32 v66, v104
	v_exp_f32_e32 v67, v106
	v_exp_f32_e32 v68, v107
	v_exp_f32_e32 v69, v0
	v_sub_f32_e32 v104, v70, v105
	v_sub_f32_e32 v106, v71, v105
	v_sub_f32_e32 v107, v72, v105
	v_sub_f32_e32 v0, v73, v105
	v_exp_f32_e32 v70, v104
	v_exp_f32_e32 v71, v106
	v_exp_f32_e32 v72, v107
	v_exp_f32_e32 v73, v0
	v_cvt_pk_bf16_f32 v166, v66, v67
	v_cvt_pk_bf16_f32 v167, v68, v69
	v_sub_f32_e32 v104, v74, v105
	v_sub_f32_e32 v106, v75, v105
	v_sub_f32_e32 v107, v76, v105
	v_sub_f32_e32 v0, v77, v105
	v_exp_f32_e32 v74, v104
	v_exp_f32_e32 v75, v106
	v_exp_f32_e32 v76, v107
	v_exp_f32_e32 v77, v0
	v_add_f32_e32 v108, v66, v70
	v_add_f32_e32 v109, v67, v71
	v_add_f32_e32 v178, v68, v72
	v_add_f32_e32 v179, v69, v73
	v_cvt_pk_bf16_f32 v168, v70, v71
	v_cvt_pk_bf16_f32 v169, v72, v73
	ds_read_b64_tr_b16 v[240:241], v174 offset:12288
	ds_read_b64_tr_b16 v[242:243], v174 offset:13312
	ds_read_b64_tr_b16 v[244:245], v175 offset:12288
	ds_read_b64_tr_b16 v[246:247], v175 offset:13312
	v_sub_f32_e32 v104, v78, v105
	v_sub_f32_e32 v106, v79, v105
	v_sub_f32_e32 v107, v80, v105
	v_sub_f32_e32 v0, v81, v105
	v_exp_f32_e32 v78, v104
	v_exp_f32_e32 v79, v106
	v_exp_f32_e32 v80, v107
	v_exp_f32_e32 v81, v0
	v_add_f32_e32 v108, v108, v74
	v_add_f32_e32 v109, v109, v75
	v_add_f32_e32 v178, v178, v76
	v_add_f32_e32 v179, v179, v77
	v_cvt_pk_bf16_f32 v170, v74, v75
	v_cvt_pk_bf16_f32 v171, v76, v77
	v_sub_f32_e32 v104, v82, v105
	v_sub_f32_e32 v106, v83, v105
	v_sub_f32_e32 v107, v84, v105
	v_sub_f32_e32 v0, v85, v105
	v_exp_f32_e32 v82, v104
	v_exp_f32_e32 v83, v106
	v_exp_f32_e32 v84, v107
	v_exp_f32_e32 v85, v0
	v_add_f32_e32 v108, v108, v78
	v_add_f32_e32 v109, v109, v79
	v_add_f32_e32 v178, v178, v80
	v_add_f32_e32 v179, v179, v81
	v_cvt_pk_bf16_f32 v172, v78, v79
	v_cvt_pk_bf16_f32 v173, v80, v81
	ds_read_b64_tr_b16 v[158:159], v174 offset:14336
	ds_read_b64_tr_b16 v[160:161], v174 offset:15360
	ds_read_b64_tr_b16 v[162:163], v175 offset:14336
	ds_read_b64_tr_b16 v[164:165], v175 offset:15360
	v_sub_f32_e32 v104, v86, v105
	v_sub_f32_e32 v106, v87, v105
	v_sub_f32_e32 v107, v88, v105
	v_sub_f32_e32 v0, v89, v105
	v_exp_f32_e32 v86, v104
	v_exp_f32_e32 v87, v106
	v_exp_f32_e32 v88, v107
	v_exp_f32_e32 v89, v0
	v_add_f32_e32 v108, v108, v82
	v_add_f32_e32 v109, v109, v83
	v_add_f32_e32 v178, v178, v84
	v_add_f32_e32 v179, v179, v85
	v_cvt_pk_bf16_f32 v248, v82, v83
	v_cvt_pk_bf16_f32 v249, v84, v85
	v_sub_f32_e32 v104, v90, v105
	v_sub_f32_e32 v106, v91, v105
	v_sub_f32_e32 v107, v92, v105
	v_sub_f32_e32 v0, v93, v105
	v_exp_f32_e32 v90, v104
	v_exp_f32_e32 v91, v106
	v_exp_f32_e32 v92, v107
	v_exp_f32_e32 v93, v0
	v_add_f32_e32 v108, v108, v86
	v_add_f32_e32 v109, v109, v87
	v_add_f32_e32 v178, v178, v88
	v_add_f32_e32 v179, v179, v89
	v_cvt_pk_bf16_f32 v250, v86, v87
	v_cvt_pk_bf16_f32 v251, v88, v89
	v_sub_f32_e32 v104, v94, v105
	v_sub_f32_e32 v106, v95, v105
	v_sub_f32_e32 v107, v96, v105
	v_sub_f32_e32 v0, v97, v105
	v_exp_f32_e32 v94, v104
	v_exp_f32_e32 v95, v106
	v_exp_f32_e32 v96, v107
	v_exp_f32_e32 v97, v0
	v_add_f32_e32 v108, v108, v90
	v_add_f32_e32 v109, v109, v91
	v_add_f32_e32 v178, v178, v92
	v_add_f32_e32 v179, v179, v93
	v_cvt_pk_bf16_f32 v126, v90, v91
	v_cvt_pk_bf16_f32 v127, v92, v93
	v_add_f32_e32 v108, v108, v94
	v_add_f32_e32 v109, v109, v95
	v_add_f32_e32 v178, v178, v96
	v_add_f32_e32 v179, v179, v97
	v_cvt_pk_bf16_f32 v128, v94, v95
	v_cvt_pk_bf16_f32 v129, v96, v97
	v_add_f32_e32 v108, v108, v109
	v_add_f32_e32 v178, v178, v179
	v_add_f32_e32 v108, v108, v178
	v_add_f32_e32 v123, v123, v108
	s_waitcnt lgkmcnt(12)
	v_mfma_f32_32x32x16_bf16 v[50:65], v[224:227], v[166:169], v[50:65]
	v_mfma_f32_32x32x16_bf16 v[34:49], v[228:231], v[166:169], v[34:49]
	s_waitcnt lgkmcnt(8)
	v_mfma_f32_32x32x16_bf16 v[50:65], v[232:235], v[170:173], v[50:65]
	v_mfma_f32_32x32x16_bf16 v[34:49], v[236:239], v[170:173], v[34:49]
	s_waitcnt lgkmcnt(4)
	v_mfma_f32_32x32x16_bf16 v[50:65], v[240:243], v[248:251], v[50:65]
	v_mfma_f32_32x32x16_bf16 v[34:49], v[244:247], v[248:251], v[34:49]
	s_waitcnt lgkmcnt(0)
	v_mfma_f32_32x32x16_bf16 v[50:65], v[158:161], v[126:129], v[50:65]
	v_mfma_f32_32x32x16_bf16 v[34:49], v[162:165], v[126:129], v[34:49]
	s_or_b32 s12, s18, s15
	s_cmp_lt_i32 s12, 0
	s_mov_b64 s[12:13], -1
	s_cbranch_scc0 .LBB0_1338
	s_and_b32 s12, s18, s15
	s_cmp_lt_i32 s12, 0
	s_mov_b64 s[12:13], -1
	s_cbranch_scc0 .LBB0_1335
	s_waitcnt vmcnt(0)
	s_mov_b64 s[12:13], 0

.LBB0_1343:
	s_add_u32 s16, s10, -1
	s_addc_u32 s17, s11, -1
	v_mov_b32_e32 v191, v123
	s_andn2_b64 vcc, exec, s[12:13]
	s_and_b64 s[10:11], s[16:17], s[10:11]
	s_cbranch_vccz .LBB0_1345
	s_branch .LBB0_1328
.Lslc_rescale:
	s_nop 1
	v_cndmask_b32_e32 v0, v124, v105, vcc
	v_sub_f32_e32 v104, v124, v0
	v_exp_f32_e32 v104, v104
	v_mov_b32_e32 v124, v0
	s_nop 0
	v_mul_f32_e32 v123, v123, v104
	v_mul_f32_e32 v34, v34, v104
	v_mul_f32_e32 v35, v35, v104
	v_mul_f32_e32 v36, v36, v104
	v_mul_f32_e32 v37, v37, v104
	v_mul_f32_e32 v38, v38, v104
	v_mul_f32_e32 v39, v39, v104
	v_mul_f32_e32 v40, v40, v104
	v_mul_f32_e32 v41, v41, v104
	v_mul_f32_e32 v42, v42, v104
	v_mul_f32_e32 v43, v43, v104
	v_mul_f32_e32 v44, v44, v104
	v_mul_f32_e32 v45, v45, v104
	v_mul_f32_e32 v46, v46, v104
	v_mul_f32_e32 v47, v47, v104
	v_mul_f32_e32 v48, v48, v104
	v_mul_f32_e32 v49, v49, v104
	v_mul_f32_e32 v50, v50, v104
	v_mul_f32_e32 v51, v51, v104
	v_mul_f32_e32 v52, v52, v104
	v_mul_f32_e32 v53, v53, v104
	v_mul_f32_e32 v54, v54, v104
	v_mul_f32_e32 v55, v55, v104
	v_mul_f32_e32 v56, v56, v104
	v_mul_f32_e32 v57, v57, v104
	v_mul_f32_e32 v58, v58, v104
	v_mul_f32_e32 v59, v59, v104
	v_mul_f32_e32 v60, v60, v104
	v_mul_f32_e32 v61, v61, v104
	v_mul_f32_e32 v62, v62, v104
	v_mul_f32_e32 v63, v63, v104
	v_mul_f32_e32 v64, v64, v104
	v_mul_f32_e32 v65, v65, v104
	s_branch .Lslc_exp
